# hynorm tile: the 16 strided y^T loads per thread issued together before one wait (were 8 dependent load pairs)
# speedup vs baseline: 1.0275x; 1.0034x over previous
.LBB0_783:
	s_and_b32 s0, s3, 0x380
	s_and_b32 s6, s12, 0xffffffc0
	v_add_u32_e32 v42, s0, v8
	s_ashr_i32 s7, s6, 31
	v_ashrrev_i32_e32 v43, 31, v42
	v_lshl_add_u64 v[40:41], s[6:7], 1, v[2:3]
	v_lshlrev_b64 v[42:43], 14, v[42:43]
	v_lshl_add_u64 v[42:43], v[40:41], 0, v[42:43]
	global_load_ushort v200, v[42:43], off
	v_add_u32_e32 v42, s0, v9
	v_ashrrev_i32_e32 v43, 31, v42
	v_lshlrev_b64 v[42:43], 14, v[42:43]
	v_lshl_add_u64 v[42:43], v[40:41], 0, v[42:43]
	global_load_ushort v201, v[42:43], off
	s_add_i32 s13, s13, s80
	s_add_i32 s12, s12, s14
	v_add_u32_e32 v42, s0, v10
	v_ashrrev_i32_e32 v43, 31, v42
	v_lshlrev_b64 v[42:43], 14, v[42:43]
	v_lshl_add_u64 v[42:43], v[40:41], 0, v[42:43]
	global_load_ushort v202, v[42:43], off
	v_add_u32_e32 v42, s0, v11
	v_ashrrev_i32_e32 v43, 31, v42
	v_lshlrev_b64 v[42:43], 14, v[42:43]
	v_lshl_add_u64 v[42:43], v[40:41], 0, v[42:43]
	global_load_ushort v203, v[42:43], off
	v_add_u32_e32 v42, s0, v12
	v_ashrrev_i32_e32 v43, 31, v42
	v_lshlrev_b64 v[42:43], 14, v[42:43]
	v_lshl_add_u64 v[42:43], v[40:41], 0, v[42:43]
	global_load_ushort v204, v[42:43], off
	v_add_u32_e32 v44, s6, v25
	v_add_u32_e32 v42, s0, v13
	v_ashrrev_i32_e32 v43, 31, v42
	v_lshlrev_b64 v[42:43], 14, v[42:43]
	v_lshl_add_u64 v[42:43], v[40:41], 0, v[42:43]
	global_load_ushort v205, v[42:43], off
	v_add_u32_e32 v42, s0, v14
	v_ashrrev_i32_e32 v43, 31, v42
	v_lshlrev_b64 v[42:43], 14, v[42:43]
	v_lshl_add_u64 v[42:43], v[40:41], 0, v[42:43]
	global_load_ushort v206, v[42:43], off
	v_add_u32_e32 v42, s0, v15
	v_ashrrev_i32_e32 v43, 31, v42
	v_lshlrev_b64 v[42:43], 14, v[42:43]
	v_lshl_add_u64 v[42:43], v[40:41], 0, v[42:43]
	global_load_ushort v207, v[42:43], off
	v_add_u32_e32 v42, s0, v16
	v_ashrrev_i32_e32 v43, 31, v42
	v_lshlrev_b64 v[42:43], 14, v[42:43]
	v_lshl_add_u64 v[42:43], v[40:41], 0, v[42:43]
	global_load_ushort v208, v[42:43], off
	v_add_u32_e32 v42, s0, v17
	v_ashrrev_i32_e32 v43, 31, v42
	v_lshlrev_b64 v[42:43], 14, v[42:43]
	v_lshl_add_u64 v[42:43], v[40:41], 0, v[42:43]
	global_load_ushort v209, v[42:43], off
	v_add_u32_e32 v42, s0, v18
	v_ashrrev_i32_e32 v43, 31, v42
	v_lshlrev_b64 v[42:43], 14, v[42:43]
	v_lshl_add_u64 v[42:43], v[40:41], 0, v[42:43]
	global_load_ushort v210, v[42:43], off
	v_add_u32_e32 v42, s0, v19
	v_ashrrev_i32_e32 v43, 31, v42
	v_lshlrev_b64 v[42:43], 14, v[42:43]
	v_lshl_add_u64 v[42:43], v[40:41], 0, v[42:43]
	global_load_ushort v211, v[42:43], off
	v_add_u32_e32 v42, s0, v20
	v_ashrrev_i32_e32 v43, 31, v42
	v_lshlrev_b64 v[42:43], 14, v[42:43]
	v_lshl_add_u64 v[42:43], v[40:41], 0, v[42:43]
	global_load_ushort v212, v[42:43], off
	v_add_u32_e32 v42, s0, v21
	v_ashrrev_i32_e32 v43, 31, v42
	v_lshlrev_b64 v[42:43], 14, v[42:43]
	v_lshl_add_u64 v[42:43], v[40:41], 0, v[42:43]
	global_load_ushort v213, v[42:43], off
	v_add_u32_e32 v42, s0, v22
	v_ashrrev_i32_e32 v43, 31, v42
	v_lshlrev_b64 v[42:43], 14, v[42:43]
	v_lshl_add_u64 v[42:43], v[40:41], 0, v[42:43]
	global_load_ushort v214, v[42:43], off
	v_add_u32_e32 v42, s0, v23
	v_ashrrev_i32_e32 v43, 31, v42
	v_lshlrev_b64 v[42:43], 14, v[42:43]
	v_lshl_add_u64 v[40:41], v[40:41], 0, v[42:43]
	global_load_ushort v215, v[40:41], off
	v_or_b32_e32 v39, s0, v0
	v_lshlrev_b32_e32 v39, 2, v39
	s_waitcnt vmcnt(0)
	v_lshlrev_b32_e32 v200, 16, v200
	ds_write_b32 v34, v200
	v_lshlrev_b32_e32 v201, 16, v201
	v_mul_f32_e32 v45, v201, v201
	v_fmac_f32_e32 v45, v200, v200
	v_lshlrev_b32_e32 v202, 16, v202
	ds_write2_b32 v35, v201, v202 offset1:65
	v_fmac_f32_e32 v45, v202, v202
	v_lshlrev_b32_e32 v203, 16, v203
	v_fmac_f32_e32 v45, v203, v203
	v_lshlrev_b32_e32 v204, 16, v204
	ds_write2_b32 v35, v203, v204 offset0:130 offset1:195
	v_fmac_f32_e32 v45, v204, v204
	v_lshlrev_b32_e32 v205, 16, v205
	v_fmac_f32_e32 v45, v205, v205
	v_lshlrev_b32_e32 v206, 16, v206
	ds_write2_b32 v36, v205, v206 offset0:4 offset1:69
	v_fmac_f32_e32 v45, v206, v206
	v_lshlrev_b32_e32 v207, 16, v207
	v_fmac_f32_e32 v45, v207, v207
	v_lshlrev_b32_e32 v208, 16, v208
	ds_write2_b32 v36, v207, v208 offset0:134 offset1:199
	v_fmac_f32_e32 v45, v208, v208
	v_lshlrev_b32_e32 v209, 16, v209
	v_fmac_f32_e32 v45, v209, v209
	v_lshlrev_b32_e32 v210, 16, v210
	ds_write2_b32 v37, v209, v210 offset0:8 offset1:73
	v_fmac_f32_e32 v45, v210, v210
	v_lshlrev_b32_e32 v211, 16, v211
	v_fmac_f32_e32 v45, v211, v211
	v_lshlrev_b32_e32 v212, 16, v212
	ds_write2_b32 v37, v211, v212 offset0:138 offset1:203
	v_fmac_f32_e32 v45, v212, v212
	v_lshlrev_b32_e32 v213, 16, v213
	v_fmac_f32_e32 v45, v213, v213
	v_lshlrev_b32_e32 v214, 16, v214
	ds_write2_b32 v38, v213, v214 offset0:12 offset1:77
	v_fmac_f32_e32 v45, v214, v214
	v_lshlrev_b32_e32 v215, 16, v215
	ds_write_b32 v35, v215 offset:3640
	v_fmac_f32_e32 v45, v215, v215
	ds_write_b32 v24, v45 offset:33280
	s_waitcnt lgkmcnt(0)
	s_barrier
	global_load_dwordx2 v[80:81], v39, s[20:21]
	s_lshl_b32 s0, s0, 1
	v_ashrrev_i32_e32 v45, 31, v44
	v_lshl_add_u64 v[82:83], v[4:5], 0, s[0:1]
	v_lshlrev_b64 v[44:45], 12, v[44:45]
	ds_read2_b64 v[40:43], v26 offset1:1
	ds_read2_b32 v[84:85], v26 offset0:65 offset1:66
	v_lshl_add_u64 v[86:87], v[82:83], 0, v[44:45]
	ds_read_b128 v[44:47], v1 offset:33280
	ds_read_b128 v[48:51], v1 offset:33296
	ds_read_b128 v[52:55], v1 offset:33536
	ds_read_b128 v[56:59], v1 offset:33792
	ds_read_b128 v[60:63], v1 offset:34048
	ds_read_b128 v[64:67], v1 offset:34304
	s_waitcnt lgkmcnt(5)
	v_pk_add_f32 v[44:45], v[44:45], 0 op_sel_hi:[1,0]
	ds_read_b128 v[68:71], v1 offset:34560
	ds_read_b128 v[72:75], v1 offset:34816
	s_waitcnt lgkmcnt(5)
	v_pk_add_f32 v[44:45], v[44:45], v[52:53]
	ds_read_b128 v[76:79], v1 offset:35072
	s_waitcnt lgkmcnt(5)
	v_pk_add_f32 v[44:45], v[44:45], v[56:57]
	v_pk_add_f32 v[46:47], v[46:47], 0 op_sel_hi:[1,0]
	s_waitcnt lgkmcnt(4)
	v_pk_add_f32 v[44:45], v[44:45], v[60:61]
	v_pk_add_f32 v[46:47], v[46:47], v[54:55]
	s_waitcnt lgkmcnt(3)
	v_pk_add_f32 v[44:45], v[44:45], v[64:65]
	v_pk_add_f32 v[46:47], v[46:47], v[58:59]
	s_waitcnt lgkmcnt(2)
	v_pk_add_f32 v[44:45], v[44:45], v[68:69]
	v_pk_add_f32 v[46:47], v[46:47], v[62:63]
	s_waitcnt lgkmcnt(1)
	v_pk_add_f32 v[44:45], v[44:45], v[72:73]
	v_pk_add_f32 v[46:47], v[46:47], v[66:67]
	s_waitcnt lgkmcnt(0)
	v_pk_add_f32 v[44:45], v[44:45], v[76:77]
	v_pk_add_f32 v[46:47], v[46:47], v[70:71]
	v_pk_fma_f32 v[44:45], v[44:45], s[2:3], v[6:7] op_sel_hi:[1,0,0]
	v_pk_add_f32 v[46:47], v[46:47], v[74:75]
	v_mul_f32_e32 v39, 0x4b800000, v44
	v_cmp_gt_f32_e64 s[4:5], s9, v44
	v_cmp_gt_f32_e32 vcc, s9, v45
	v_pk_add_f32 v[46:47], v[46:47], v[78:79]
	v_cndmask_b32_e64 v39, v44, v39, s[4:5]
	v_rsq_f32_e32 v39, v39
	v_pk_fma_f32 v[46:47], v[46:47], s[2:3], v[6:7] op_sel_hi:[1,0,0]
	v_pk_add_f32 v[48:49], v[48:49], 0 op_sel_hi:[1,0]
	v_mul_f32_e32 v44, 0x45800000, v39
	v_cndmask_b32_e64 v39, v39, v44, s[4:5]
	v_mul_f32_e32 v40, v40, v39
	v_mul_f32_e32 v39, v84, v39
	v_cmp_gt_f32_e64 s[4:5], s9, v46
	s_waitcnt vmcnt(0)
	v_mul_f32_e32 v40, v80, v40
	v_mul_f32_e32 v39, v81, v39
	v_bfe_u32 v44, v40, 16, 1
	v_add3_u32 v40, v40, v44, s10
	v_bfe_u32 v44, v39, 16, 1
	v_lshrrev_b32_e32 v40, 16, v40
	v_add3_u32 v39, v39, v44, s10
	v_and_or_b32 v39, v39, s11, v40
	global_store_dword v[86:87], v39, off
	v_mul_f32_e32 v39, 0x4b800000, v45
	v_cndmask_b32_e32 v39, v45, v39, vcc
	v_rsq_f32_e32 v39, v39
	v_add_u32_e32 v44, s6, v28
	v_ashrrev_i32_e32 v45, 31, v44
	v_lshlrev_b64 v[44:45], 12, v[44:45]
	v_mul_f32_e32 v40, 0x45800000, v39
	v_cndmask_b32_e32 v39, v39, v40, vcc
	v_mul_f32_e32 v40, v41, v39
	v_mul_f32_e32 v40, v80, v40
	v_mul_f32_e32 v39, v85, v39
	v_mul_f32_e32 v39, v81, v39
	v_bfe_u32 v41, v40, 16, 1
	v_add3_u32 v40, v40, v41, s10
	v_bfe_u32 v41, v39, 16, 1
	v_lshrrev_b32_e32 v40, 16, v40
	v_add3_u32 v39, v39, v41, s10
	v_and_or_b32 v39, v39, s11, v40
	v_add_u32_e32 v40, s6, v27
	v_ashrrev_i32_e32 v41, 31, v40
	v_lshlrev_b64 v[40:41], 12, v[40:41]
	v_lshl_add_u64 v[40:41], v[82:83], 0, v[40:41]
	global_store_dword v[40:41], v39, off
	v_mul_f32_e32 v39, 0x4b800000, v46
	v_cndmask_b32_e64 v39, v46, v39, s[4:5]
	v_rsq_f32_e32 v39, v39
	ds_read2_b32 v[40:41], v26 offset0:67 offset1:68
	v_lshl_add_u64 v[44:45], v[82:83], 0, v[44:45]
	v_cmp_gt_f32_e32 vcc, s9, v47
	v_mul_f32_e32 v46, 0x45800000, v39
	v_cndmask_b32_e64 v39, v39, v46, s[4:5]
	v_mul_f32_e32 v42, v42, v39
	v_mul_f32_e32 v42, v80, v42
	s_waitcnt lgkmcnt(0)
	v_mul_f32_e32 v39, v40, v39
	v_mul_f32_e32 v39, v81, v39
	v_bfe_u32 v40, v42, 16, 1
	v_add3_u32 v40, v42, v40, s10
	v_bfe_u32 v42, v39, 16, 1
	v_lshrrev_b32_e32 v40, 16, v40
	v_add3_u32 v39, v39, v42, s10
	v_and_or_b32 v39, v39, s11, v40
	global_store_dword v[44:45], v39, off
	v_mul_f32_e32 v39, 0x4b800000, v47
	v_cndmask_b32_e32 v39, v47, v39, vcc
	v_rsq_f32_e32 v39, v39
	v_add_u32_e32 v44, s6, v30
	v_ashrrev_i32_e32 v45, 31, v44
	v_lshlrev_b64 v[44:45], 12, v[44:45]
	v_mul_f32_e32 v40, 0x45800000, v39
	v_cndmask_b32_e32 v39, v39, v40, vcc
	v_mul_f32_e32 v40, v43, v39
	v_mul_f32_e32 v40, v80, v40
	v_mul_f32_e32 v39, v41, v39
	v_mul_f32_e32 v39, v81, v39
	v_bfe_u32 v41, v40, 16, 1
	v_add3_u32 v40, v40, v41, s10
	v_bfe_u32 v41, v39, 16, 1
	v_lshrrev_b32_e32 v40, 16, v40
	v_add3_u32 v39, v39, v41, s10
	v_and_or_b32 v39, v39, s11, v40
	v_add_u32_e32 v40, s6, v29
	v_ashrrev_i32_e32 v41, 31, v40
	v_lshlrev_b64 v[40:41], 12, v[40:41]
	v_lshl_add_u64 v[40:41], v[82:83], 0, v[40:41]
	global_store_dword v[40:41], v39, off
	ds_read2_b64 v[40:43], v26 offset0:2 offset1:3
	ds_read2_b32 v[76:77], v26 offset0:69 offset1:70
	v_lshl_add_u64 v[78:79], v[82:83], 0, v[44:45]
	ds_read_b128 v[44:47], v1 offset:33552
	ds_read_b128 v[52:55], v1 offset:33808
	ds_read_b128 v[56:59], v1 offset:34064
	ds_read_b128 v[60:63], v1 offset:34320
	ds_read_b128 v[64:67], v1 offset:34576
	ds_read_b128 v[68:71], v1 offset:34832
	s_waitcnt lgkmcnt(5)
	v_pk_add_f32 v[44:45], v[48:49], v[44:45]
	ds_read_b128 v[72:75], v1 offset:35088
	s_waitcnt lgkmcnt(5)
	v_pk_add_f32 v[44:45], v[44:45], v[52:53]
	v_pk_add_f32 v[48:49], v[50:51], 0 op_sel_hi:[1,0]
	s_waitcnt lgkmcnt(4)
	v_pk_add_f32 v[44:45], v[44:45], v[56:57]
	v_pk_add_f32 v[46:47], v[48:49], v[46:47]
	s_waitcnt lgkmcnt(3)
	v_pk_add_f32 v[44:45], v[44:45], v[60:61]
	v_pk_add_f32 v[46:47], v[46:47], v[54:55]
	s_waitcnt lgkmcnt(2)
	v_pk_add_f32 v[44:45], v[44:45], v[64:65]
	v_pk_add_f32 v[46:47], v[46:47], v[58:59]
	s_waitcnt lgkmcnt(1)
	v_pk_add_f32 v[44:45], v[44:45], v[68:69]
	v_pk_add_f32 v[46:47], v[46:47], v[62:63]
	s_waitcnt lgkmcnt(0)
	v_pk_add_f32 v[44:45], v[44:45], v[72:73]
	v_pk_add_f32 v[46:47], v[46:47], v[66:67]
	v_pk_fma_f32 v[44:45], v[44:45], s[2:3], v[6:7] op_sel_hi:[1,0,0]
	v_pk_add_f32 v[46:47], v[46:47], v[70:71]
	v_mul_f32_e32 v39, 0x4b800000, v44
	v_cmp_gt_f32_e64 s[4:5], s9, v44
	v_cmp_gt_f32_e32 vcc, s9, v45
	v_pk_add_f32 v[46:47], v[46:47], v[74:75]
	v_cndmask_b32_e64 v39, v44, v39, s[4:5]
	v_rsq_f32_e32 v39, v39
	v_pk_fma_f32 v[46:47], v[46:47], s[2:3], v[6:7] op_sel_hi:[1,0,0]
	s_add_i32 s3, s3, s8
	s_cmpk_gt_i32 s13, 0x3ff
	v_mul_f32_e32 v44, 0x45800000, v39
	v_cndmask_b32_e64 v39, v39, v44, s[4:5]
	v_mul_f32_e32 v40, v40, v39
	v_mul_f32_e32 v40, v80, v40
	v_mul_f32_e32 v39, v76, v39
	v_mul_f32_e32 v39, v81, v39
	v_bfe_u32 v44, v40, 16, 1
	v_add3_u32 v40, v40, v44, s10
	v_bfe_u32 v44, v39, 16, 1
	v_lshrrev_b32_e32 v40, 16, v40
	v_add3_u32 v39, v39, v44, s10
	v_and_or_b32 v39, v39, s11, v40
	global_store_dword v[78:79], v39, off
	v_mul_f32_e32 v39, 0x4b800000, v45
	v_cndmask_b32_e32 v39, v45, v39, vcc
	v_rsq_f32_e32 v39, v39
	v_cmp_gt_f32_e64 s[4:5], s9, v46
	v_add_u32_e32 v44, s6, v32
	v_ashrrev_i32_e32 v45, 31, v44
	v_mul_f32_e32 v40, 0x45800000, v39
	v_cndmask_b32_e32 v39, v39, v40, vcc
	v_mul_f32_e32 v40, v41, v39
	v_mul_f32_e32 v40, v80, v40
	v_mul_f32_e32 v39, v77, v39
	v_mul_f32_e32 v39, v81, v39
	v_bfe_u32 v41, v40, 16, 1
	v_add3_u32 v40, v40, v41, s10
	v_bfe_u32 v41, v39, 16, 1
	v_lshrrev_b32_e32 v40, 16, v40
	v_add3_u32 v39, v39, v41, s10
	v_and_or_b32 v39, v39, s11, v40
	v_add_u32_e32 v40, s6, v31
	v_ashrrev_i32_e32 v41, 31, v40
	v_lshlrev_b64 v[40:41], 12, v[40:41]
	v_lshl_add_u64 v[40:41], v[82:83], 0, v[40:41]
	global_store_dword v[40:41], v39, off
	v_mul_f32_e32 v39, 0x4b800000, v46
	v_cndmask_b32_e64 v39, v46, v39, s[4:5]
	v_rsq_f32_e32 v39, v39
	ds_read2_b32 v[40:41], v26 offset0:71 offset1:72
	v_lshlrev_b64 v[44:45], 12, v[44:45]
	v_lshl_add_u64 v[44:45], v[82:83], 0, v[44:45]
	v_mul_f32_e32 v46, 0x45800000, v39
	v_cndmask_b32_e64 v39, v39, v46, s[4:5]
	v_mul_f32_e32 v42, v42, v39
	v_mul_f32_e32 v42, v80, v42
	s_waitcnt lgkmcnt(0)
	v_mul_f32_e32 v39, v40, v39
	v_mul_f32_e32 v39, v81, v39
	v_bfe_u32 v40, v42, 16, 1
	v_add3_u32 v40, v42, v40, s10
	v_bfe_u32 v42, v39, 16, 1
	v_lshrrev_b32_e32 v40, 16, v40
	v_add3_u32 v39, v39, v42, s10
	v_and_or_b32 v39, v39, s11, v40
	v_cmp_gt_f32_e32 vcc, s9, v47
	global_store_dword v[44:45], v39, off
	v_mul_f32_e32 v39, 0x4b800000, v47
	v_cndmask_b32_e32 v39, v47, v39, vcc
	v_rsq_f32_e32 v39, v39
	s_nop 0
	v_mul_f32_e32 v40, 0x45800000, v39
	v_cndmask_b32_e32 v39, v39, v40, vcc
	v_mul_f32_e32 v40, v43, v39
	v_mul_f32_e32 v40, v80, v40
	v_mul_f32_e32 v39, v41, v39
	v_mul_f32_e32 v39, v81, v39
	v_bfe_u32 v41, v40, 16, 1
	v_add3_u32 v40, v40, v41, s10
	v_bfe_u32 v41, v39, 16, 1
	v_lshrrev_b32_e32 v40, 16, v40
	v_add3_u32 v39, v39, v41, s10
	v_and_or_b32 v39, v39, s11, v40
	v_add_u32_e32 v40, s6, v33
	v_ashrrev_i32_e32 v41, 31, v40
	v_lshlrev_b64 v[40:41], 12, v[40:41]
	v_lshl_add_u64 v[40:41], v[82:83], 0, v[40:41]
	global_store_dword v[40:41], v39, off
	s_barrier
	s_cbranch_scc0 .LBB0_783
